# instruction selection: row sums in the interior attention steps as four scalar f32 add chains instead of v_pk_add_f32
# speedup vs baseline: 1.0032x; 1.0032x over previous
; __device__ __forceinline__ unsigned cvt_pk_bf16(float lo, float hi) { unsigned r; asm volatile("v_cvt_pk_bf16_f32 %0, %1, %2" : "=v"(r) : "v"(lo), "v"(hi)); return r; }
; __device__ __forceinline__ int swz(int R) { return (R & 2) | ((R & 8) >> 1); }
; template <int CGM>
; __device__ __forceinline__ void pv2(f32x4 (&o)[2][4], const float (&p)[2][4][4], const unsigned char* Vs, int r, int fq) {
;     bf16x8 pb[2][2];
; #pragma unroll
;     for (int cg_ = 0; cg_ < 2; ++cg_) if ((CGM >> cg_) & 1)
; #pragma unroll
;         for (int kc = 0; kc < 2; ++kc) {
;             u32x4 w; w.x = cvt_pk_bf16(p[cg_][2 * kc][0], p[cg_][2 * kc][1]); w.y = cvt_pk_bf16(p[cg_][2 * kc][2], p[cg_][2 * kc][3]);
;             w.z = cvt_pk_bf16(p[cg_][2 * kc + 1][0], p[cg_][2 * kc + 1][1]); w.w = cvt_pk_bf16(p[cg_][2 * kc + 1][2], p[cg_][2 * kc + 1][3]);
;             pb[cg_][kc] = __builtin_bit_cast(bf16x8, w);
;         }
; #pragma unroll
;     for (int df = 0; df < 4; ++df)
; #pragma unroll
;         for (int kc = 0; kc < 2; ++kc) {
;             const int R = prow(df, r);
;             const bf16x8 vf = *(const bf16x8*)(Vs + R * 128 + (((4 * kc + fq) ^ swz(R)) << 4));
;             if (CGM & 1) o[0][df] = __builtin_amdgcn_mfma_f32_16x16x32_bf16(vf, pb[0][kc], o[0][df], 0, 0, 0);
;             if (CGM & 2) o[1][df] = __builtin_amdgcn_mfma_f32_16x16x32_bf16(vf, pb[1][kc], o[1][df], 0, 0, 0);
;         }
; }
; template <int CGM>
; __device__ __forceinline__ void step_int(const bf16x8 (&kf)[4][2], const bf16x8 (&q)[2][2], float farb, const bool (&selq)[2],
;                                          float (&m)[2], float (&l)[2], f32x4 (&o)[2][4], const unsigned char* Vs, int r, int fq) {
;     ...
;     float p[2][4][4];
; #pragma unroll
;     for (int cg_ = 0; cg_ < 2; ++cg_) if ((CGM >> cg_) & 1) {
;         float rs = 0.f;
; #pragma unroll
;         for (int f = 0; f < 4; ++f)
; #pragma unroll
;             for (int i = 0; i < 4; ++i) { const float pe = __builtin_amdgcn_exp2f(s[cg_][f][i]); p[cg_][f][i] = pe; rs += pe; }
;         l[cg_] += rs;
;     }
;     pv2<CGM>(o, p, Vs, r, fq);
.Lsel_c3_e0:
	v_exp_f32_e32 v232, v92
	v_exp_f32_e32 v233, v93
	v_exp_f32_e32 v234, v94
	v_exp_f32_e32 v235, v95
	v_exp_f32_e32 v236, v96
	v_exp_f32_e32 v237, v97
	v_exp_f32_e32 v238, v98
	v_exp_f32_e32 v239, v99
	ds_read_b128 v[84:87], v142 offset:8192
	ds_read_b128 v[76:79], v142 offset:8704
	ds_read_b128 v[68:71], v142 offset:12288
	ds_read_b128 v[64:67], v142 offset:12800
	v_exp_f32_e32 v240, v100
	v_exp_f32_e32 v241, v101
	v_exp_f32_e32 v242, v102
	v_exp_f32_e32 v243, v103
	v_exp_f32_e32 v244, v104
	v_exp_f32_e32 v245, v105
	v_exp_f32_e32 v246, v106
	v_exp_f32_e32 v247, v107
	v_add_f32_e32 v128, v232, v233
	v_add_f32_e32 v129, v234, v235
	v_add_f32_e32 v130, v236, v237
	v_add_f32_e32 v131, v238, v239
	v_add_f32_e32 v128, v128, v240
	v_add_f32_e32 v129, v129, v241
	v_add_f32_e32 v130, v130, v242
	v_add_f32_e32 v131, v131, v243
	v_add_f32_e32 v128, v128, v244
	v_add_f32_e32 v129, v129, v245
	v_add_f32_e32 v130, v130, v246
	v_add_f32_e32 v131, v131, v247
	v_add_f32_e32 v128, v128, v129
	v_add_f32_e32 v130, v130, v131
	v_add_f32_e32 v130, v130, v128
	v_cmp_lt_f32_e32 vcc, 0x42800000, v130
	s_cbranch_vccnz .Lsel_c3_s0
	v_add_f32_e32 v127, v127, v130
	v_cvt_pk_bf16_f32 v92, v232, v233
	v_cvt_pk_bf16_f32 v93, v234, v235
	v_cvt_pk_bf16_f32 v94, v236, v237
	v_cvt_pk_bf16_f32 v95, v238, v239
	v_cvt_pk_bf16_f32 v96, v240, v241
	v_cvt_pk_bf16_f32 v97, v242, v243
	v_cvt_pk_bf16_f32 v98, v244, v245
	v_cvt_pk_bf16_f32 v99, v246, v247
.Lsel_c3_e1:
	v_exp_f32_e32 v232, v108
	v_exp_f32_e32 v233, v109
	v_exp_f32_e32 v234, v110
	v_exp_f32_e32 v235, v111
	v_exp_f32_e32 v236, v112
	v_exp_f32_e32 v237, v113
	v_exp_f32_e32 v238, v114
	v_exp_f32_e32 v239, v115
	v_exp_f32_e32 v240, v116
	v_exp_f32_e32 v241, v117
	v_exp_f32_e32 v242, v118
	v_exp_f32_e32 v243, v119
	v_exp_f32_e32 v244, v120
	v_exp_f32_e32 v245, v121
	v_exp_f32_e32 v246, v122
	v_exp_f32_e32 v247, v123
	v_add_f32_e32 v144, v232, v233
	v_add_f32_e32 v145, v234, v235
	v_add_f32_e32 v146, v236, v237
	v_add_f32_e32 v147, v238, v239
	v_add_f32_e32 v144, v144, v240
	v_add_f32_e32 v145, v145, v241
	v_add_f32_e32 v146, v146, v242
	v_add_f32_e32 v147, v147, v243
	v_add_f32_e32 v144, v144, v244
	v_add_f32_e32 v145, v145, v245
	v_add_f32_e32 v146, v146, v246
	v_add_f32_e32 v147, v147, v247
	v_add_f32_e32 v144, v144, v145
	v_add_f32_e32 v146, v146, v147
	v_add_f32_e32 v146, v146, v144
	v_cmp_lt_f32_e32 vcc, 0x42800000, v146
	s_cbranch_vccnz .Lsel_c3_s1
	v_add_f32_e32 v126, v126, v146
	v_cvt_pk_bf16_f32 v108, v232, v233
	v_cvt_pk_bf16_f32 v109, v234, v235
	v_cvt_pk_bf16_f32 v110, v236, v237
	v_cvt_pk_bf16_f32 v111, v238, v239
	v_cvt_pk_bf16_f32 v112, v240, v241
	v_cvt_pk_bf16_f32 v113, v242, v243
	v_cvt_pk_bf16_f32 v114, v244, v245
	v_cvt_pk_bf16_f32 v115, v246, v247
	s_waitcnt lgkmcnt(0)
	s_nop 0
	v_mfma_f32_16x16x32_bf16 v[56:59], v[88:91], v[92:95], v[56:59]
	v_mfma_f32_16x16x32_bf16 v[40:43], v[88:91], v[108:111], v[40:43]
	v_mfma_f32_16x16x32_bf16 v[52:55], v[80:83], v[92:95], v[52:55]
	v_mfma_f32_16x16x32_bf16 v[28:31], v[80:83], v[108:111], v[28:31]
	v_mfma_f32_16x16x32_bf16 v[48:51], v[72:75], v[92:95], v[48:51]
	v_mfma_f32_16x16x32_bf16 v[24:27], v[72:75], v[108:111], v[24:27]
	v_mfma_f32_16x16x32_bf16 v[44:47], v[60:63], v[92:95], v[44:47]
	v_mfma_f32_16x16x32_bf16 v[20:23], v[60:63], v[108:111], v[20:23]
	v_mfma_f32_16x16x32_bf16 v[56:59], v[84:87], v[96:99], v[56:59]
	v_mfma_f32_16x16x32_bf16 v[40:43], v[84:87], v[112:115], v[40:43]
	v_mfma_f32_16x16x32_bf16 v[52:55], v[76:79], v[96:99], v[52:55]
	v_mfma_f32_16x16x32_bf16 v[28:31], v[76:79], v[112:115], v[28:31]
	v_mfma_f32_16x16x32_bf16 v[48:51], v[68:71], v[96:99], v[48:51]
	v_mfma_f32_16x16x32_bf16 v[24:27], v[68:71], v[112:115], v[24:27]
	v_mfma_f32_16x16x32_bf16 v[44:47], v[64:67], v[96:99], v[44:47]
	v_mfma_f32_16x16x32_bf16 v[20:23], v[64:67], v[112:115], v[20:23]
	s_branch .LBB0_2481

; __device__ __forceinline__ unsigned cvt_pk_bf16(float lo, float hi) { unsigned r; asm volatile("v_cvt_pk_bf16_f32 %0, %1, %2" : "=v"(r) : "v"(lo), "v"(hi)); return r; }
; __device__ __forceinline__ int swz(int R) { return (R & 2) | ((R & 8) >> 1); }
; template <int CGM>
; __device__ __forceinline__ void pv2(f32x4 (&o)[2][4], const float (&p)[2][4][4], const unsigned char* Vs, int r, int fq) {
;     bf16x8 pb[2][2];
; #pragma unroll
;     for (int cg_ = 0; cg_ < 2; ++cg_) if ((CGM >> cg_) & 1)
; #pragma unroll
;         for (int kc = 0; kc < 2; ++kc) {
;             u32x4 w; w.x = cvt_pk_bf16(p[cg_][2 * kc][0], p[cg_][2 * kc][1]); w.y = cvt_pk_bf16(p[cg_][2 * kc][2], p[cg_][2 * kc][3]);
;             w.z = cvt_pk_bf16(p[cg_][2 * kc + 1][0], p[cg_][2 * kc + 1][1]); w.w = cvt_pk_bf16(p[cg_][2 * kc + 1][2], p[cg_][2 * kc + 1][3]);
;             pb[cg_][kc] = __builtin_bit_cast(bf16x8, w);
;         }
; #pragma unroll
;     for (int df = 0; df < 4; ++df)
; #pragma unroll
;         for (int kc = 0; kc < 2; ++kc) {
;             const int R = prow(df, r);
;             const bf16x8 vf = *(const bf16x8*)(Vs + R * 128 + (((4 * kc + fq) ^ swz(R)) << 4));
;             if (CGM & 1) o[0][df] = __builtin_amdgcn_mfma_f32_16x16x32_bf16(vf, pb[0][kc], o[0][df], 0, 0, 0);
;             if (CGM & 2) o[1][df] = __builtin_amdgcn_mfma_f32_16x16x32_bf16(vf, pb[1][kc], o[1][df], 0, 0, 0);
;         }
; }
; template <int CGM>
; __device__ __forceinline__ void step_int(const bf16x8 (&kf)[4][2], const bf16x8 (&q)[2][2], float farb, const bool (&selq)[2],
;                                          float (&m)[2], float (&l)[2], f32x4 (&o)[2][4], const unsigned char* Vs, int r, int fq) {
;     ...
;     float p[2][4][4];
; #pragma unroll
;     for (int cg_ = 0; cg_ < 2; ++cg_) if ((CGM >> cg_) & 1) {
;         float rs = 0.f;
; #pragma unroll
;         for (int f = 0; f < 4; ++f)
; #pragma unroll
;             for (int i = 0; i < 4; ++i) { const float pe = __builtin_amdgcn_exp2f(s[cg_][f][i]); p[cg_][f][i] = pe; rs += pe; }
;         l[cg_] += rs;
;     }
;     pv2<CGM>(o, p, Vs, r, fq);
.Lsel_c1_e0:
	v_exp_f32_e32 v232, v92
	v_exp_f32_e32 v233, v93
	v_exp_f32_e32 v234, v94
	v_exp_f32_e32 v235, v95
	v_exp_f32_e32 v236, v96
	v_exp_f32_e32 v237, v97
	v_exp_f32_e32 v238, v98
	v_exp_f32_e32 v239, v99
	ds_read_b128 v[84:87], v142 offset:8192
	ds_read_b128 v[76:79], v142 offset:8704
	ds_read_b128 v[68:71], v142 offset:12288
	ds_read_b128 v[64:67], v142 offset:12800
	v_exp_f32_e32 v240, v100
	v_exp_f32_e32 v241, v101
	v_exp_f32_e32 v242, v102
	v_exp_f32_e32 v243, v103
	v_exp_f32_e32 v244, v104
	v_exp_f32_e32 v245, v105
	v_exp_f32_e32 v246, v106
	v_exp_f32_e32 v247, v107
	v_add_f32_e32 v128, v232, v233
	v_add_f32_e32 v129, v234, v235
	v_add_f32_e32 v130, v236, v237
	v_add_f32_e32 v131, v238, v239
	v_add_f32_e32 v128, v128, v240
	v_add_f32_e32 v129, v129, v241
	v_add_f32_e32 v130, v130, v242
	v_add_f32_e32 v131, v131, v243
	v_add_f32_e32 v128, v128, v244
	v_add_f32_e32 v129, v129, v245
	v_add_f32_e32 v130, v130, v246
	v_add_f32_e32 v131, v131, v247
	v_add_f32_e32 v128, v128, v129
	v_add_f32_e32 v130, v130, v131
	v_add_f32_e32 v130, v130, v128
	v_cmp_lt_f32_e32 vcc, 0x42800000, v130
	s_cbranch_vccnz .Lsel_c1_s0
	v_add_f32_e32 v127, v127, v130
	v_cvt_pk_bf16_f32 v92, v232, v233
	v_cvt_pk_bf16_f32 v93, v234, v235
	v_cvt_pk_bf16_f32 v94, v236, v237
	v_cvt_pk_bf16_f32 v95, v238, v239
	v_cvt_pk_bf16_f32 v96, v240, v241
	v_cvt_pk_bf16_f32 v97, v242, v243
	v_cvt_pk_bf16_f32 v98, v244, v245
	v_cvt_pk_bf16_f32 v99, v246, v247
	s_waitcnt lgkmcnt(0)
	s_nop 0
	v_mfma_f32_16x16x32_bf16 v[56:59], v[88:91], v[92:95], v[56:59]
	v_mfma_f32_16x16x32_bf16 v[52:55], v[80:83], v[92:95], v[52:55]
	v_mfma_f32_16x16x32_bf16 v[48:51], v[72:75], v[92:95], v[48:51]
	v_mfma_f32_16x16x32_bf16 v[44:47], v[60:63], v[92:95], v[44:47]
	v_mfma_f32_16x16x32_bf16 v[56:59], v[84:87], v[96:99], v[56:59]
	v_mfma_f32_16x16x32_bf16 v[52:55], v[76:79], v[96:99], v[52:55]
	v_mfma_f32_16x16x32_bf16 v[48:51], v[68:71], v[96:99], v[48:51]
	v_mfma_f32_16x16x32_bf16 v[44:47], v[64:67], v[96:99], v[44:47]
	s_branch .LBB0_2481

; __device__ __forceinline__ unsigned cvt_pk_bf16(float lo, float hi) { unsigned r; asm volatile("v_cvt_pk_bf16_f32 %0, %1, %2" : "=v"(r) : "v"(lo), "v"(hi)); return r; }
; __device__ __forceinline__ int swz(int R) { return (R & 2) | ((R & 8) >> 1); }
; template <int CGM>
; __device__ __forceinline__ void pv2(f32x4 (&o)[2][4], const float (&p)[2][4][4], const unsigned char* Vs, int r, int fq) {
;     bf16x8 pb[2][2];
; #pragma unroll
;     for (int cg_ = 0; cg_ < 2; ++cg_) if ((CGM >> cg_) & 1)
; #pragma unroll
;         for (int kc = 0; kc < 2; ++kc) {
;             u32x4 w; w.x = cvt_pk_bf16(p[cg_][2 * kc][0], p[cg_][2 * kc][1]); w.y = cvt_pk_bf16(p[cg_][2 * kc][2], p[cg_][2 * kc][3]);
;             w.z = cvt_pk_bf16(p[cg_][2 * kc + 1][0], p[cg_][2 * kc + 1][1]); w.w = cvt_pk_bf16(p[cg_][2 * kc + 1][2], p[cg_][2 * kc + 1][3]);
;             pb[cg_][kc] = __builtin_bit_cast(bf16x8, w);
;         }
; #pragma unroll
;     for (int df = 0; df < 4; ++df)
; #pragma unroll
;         for (int kc = 0; kc < 2; ++kc) {
;             const int R = prow(df, r);
;             const bf16x8 vf = *(const bf16x8*)(Vs + R * 128 + (((4 * kc + fq) ^ swz(R)) << 4));
;             if (CGM & 1) o[0][df] = __builtin_amdgcn_mfma_f32_16x16x32_bf16(vf, pb[0][kc], o[0][df], 0, 0, 0);
;             if (CGM & 2) o[1][df] = __builtin_amdgcn_mfma_f32_16x16x32_bf16(vf, pb[1][kc], o[1][df], 0, 0, 0);
;         }
; }
; template <int CGM>
; __device__ __forceinline__ void step_int(const bf16x8 (&kf)[4][2], const bf16x8 (&q)[2][2], float farb, const bool (&selq)[2],
;                                          float (&m)[2], float (&l)[2], f32x4 (&o)[2][4], const unsigned char* Vs, int r, int fq) {
;     ...
;     float p[2][4][4];
; #pragma unroll
;     for (int cg_ = 0; cg_ < 2; ++cg_) if ((CGM >> cg_) & 1) {
;         float rs = 0.f;
; #pragma unroll
;         for (int f = 0; f < 4; ++f)
; #pragma unroll
;             for (int i = 0; i < 4; ++i) { const float pe = __builtin_amdgcn_exp2f(s[cg_][f][i]); p[cg_][f][i] = pe; rs += pe; }
;         l[cg_] += rs;
;     }
;     pv2<CGM>(o, p, Vs, r, fq);
.Lsel_c2_e1:
	v_exp_f32_e32 v232, v108
	v_exp_f32_e32 v233, v109
	v_exp_f32_e32 v234, v110
	v_exp_f32_e32 v235, v111
	v_exp_f32_e32 v236, v112
	v_exp_f32_e32 v237, v113
	v_exp_f32_e32 v238, v114
	v_exp_f32_e32 v239, v115
	ds_read_b128 v[84:87], v142 offset:8192
	ds_read_b128 v[76:79], v142 offset:8704
	ds_read_b128 v[68:71], v142 offset:12288
	ds_read_b128 v[64:67], v142 offset:12800
	v_exp_f32_e32 v240, v116
	v_exp_f32_e32 v241, v117
	v_exp_f32_e32 v242, v118
	v_exp_f32_e32 v243, v119
	v_exp_f32_e32 v244, v120
	v_exp_f32_e32 v245, v121
	v_exp_f32_e32 v246, v122
	v_exp_f32_e32 v247, v123
	v_add_f32_e32 v144, v232, v233
	v_add_f32_e32 v145, v234, v235
	v_add_f32_e32 v146, v236, v237
	v_add_f32_e32 v147, v238, v239
	v_add_f32_e32 v144, v144, v240
	v_add_f32_e32 v145, v145, v241
	v_add_f32_e32 v146, v146, v242
	v_add_f32_e32 v147, v147, v243
	v_add_f32_e32 v144, v144, v244
	v_add_f32_e32 v145, v145, v245
	v_add_f32_e32 v146, v146, v246
	v_add_f32_e32 v147, v147, v247
	v_add_f32_e32 v144, v144, v145
	v_add_f32_e32 v146, v146, v147
	v_add_f32_e32 v146, v146, v144
	v_cmp_lt_f32_e32 vcc, 0x42800000, v146
	s_cbranch_vccnz .Lsel_c2_s1
	v_add_f32_e32 v126, v126, v146
	v_cvt_pk_bf16_f32 v108, v232, v233
	v_cvt_pk_bf16_f32 v109, v234, v235
	v_cvt_pk_bf16_f32 v110, v236, v237
	v_cvt_pk_bf16_f32 v111, v238, v239
	v_cvt_pk_bf16_f32 v112, v240, v241
	v_cvt_pk_bf16_f32 v113, v242, v243
	v_cvt_pk_bf16_f32 v114, v244, v245
	v_cvt_pk_bf16_f32 v115, v246, v247
	s_waitcnt lgkmcnt(0)
	s_nop 0
	v_mfma_f32_16x16x32_bf16 v[40:43], v[88:91], v[108:111], v[40:43]
	v_mfma_f32_16x16x32_bf16 v[28:31], v[80:83], v[108:111], v[28:31]
	v_mfma_f32_16x16x32_bf16 v[24:27], v[72:75], v[108:111], v[24:27]
	v_mfma_f32_16x16x32_bf16 v[20:23], v[60:63], v[108:111], v[20:23]
	v_mfma_f32_16x16x32_bf16 v[40:43], v[84:87], v[112:115], v[40:43]
	v_mfma_f32_16x16x32_bf16 v[28:31], v[76:79], v[112:115], v[28:31]
	v_mfma_f32_16x16x32_bf16 v[24:27], v[68:71], v[112:115], v[24:27]
	v_mfma_f32_16x16x32_bf16 v[20:23], v[64:67], v[112:115], v[20:23]
	s_branch .LBB0_2481

; __device__ __forceinline__ unsigned cvt_pk_bf16(float lo, float hi) { unsigned r; asm volatile("v_cvt_pk_bf16_f32 %0, %1, %2" : "=v"(r) : "v"(lo), "v"(hi)); return r; }
; __device__ __forceinline__ int swz(int R) { return (R & 2) | ((R & 8) >> 1); }
; template <int CGM>
; __device__ __forceinline__ void pv2(f32x4 (&o)[2][4], const float (&p)[2][4][4], const unsigned char* Vs, int r, int fq) {
;     bf16x8 pb[2][2];
; #pragma unroll
;     for (int cg_ = 0; cg_ < 2; ++cg_) if ((CGM >> cg_) & 1)
; #pragma unroll
;         for (int kc = 0; kc < 2; ++kc) {
;             u32x4 w; w.x = cvt_pk_bf16(p[cg_][2 * kc][0], p[cg_][2 * kc][1]); w.y = cvt_pk_bf16(p[cg_][2 * kc][2], p[cg_][2 * kc][3]);
;             w.z = cvt_pk_bf16(p[cg_][2 * kc + 1][0], p[cg_][2 * kc + 1][1]); w.w = cvt_pk_bf16(p[cg_][2 * kc + 1][2], p[cg_][2 * kc + 1][3]);
;             pb[cg_][kc] = __builtin_bit_cast(bf16x8, w);
;         }
; #pragma unroll
;     for (int df = 0; df < 4; ++df)
; #pragma unroll
;         for (int kc = 0; kc < 2; ++kc) {
;             const int R = prow(df, r);
;             const bf16x8 vf = *(const bf16x8*)(Vs + R * 128 + (((4 * kc + fq) ^ swz(R)) << 4));
;             if (CGM & 1) o[0][df] = __builtin_amdgcn_mfma_f32_16x16x32_bf16(vf, pb[0][kc], o[0][df], 0, 0, 0);
;             if (CGM & 2) o[1][df] = __builtin_amdgcn_mfma_f32_16x16x32_bf16(vf, pb[1][kc], o[1][df], 0, 0, 0);
;         }
; }
; template <int CGM>
; __device__ __forceinline__ void step_int(const bf16x8 (&kf)[4][2], const bf16x8 (&q)[2][2], float farb, const bool (&selq)[2],
;                                          float (&m)[2], float (&l)[2], f32x4 (&o)[2][4], const unsigned char* Vs, int r, int fq) {
;     ...
;     float p[2][4][4];
; #pragma unroll
;     for (int cg_ = 0; cg_ < 2; ++cg_) if ((CGM >> cg_) & 1) {
;         float rs = 0.f;
; #pragma unroll
;         for (int f = 0; f < 4; ++f)
; #pragma unroll
;             for (int i = 0; i < 4; ++i) { const float pe = __builtin_amdgcn_exp2f(s[cg_][f][i]); p[cg_][f][i] = pe; rs += pe; }
;         l[cg_] += rs;
;     }
;     pv2<CGM>(o, p, Vs, r, fq);
.Lwin_int_e0:
	v_exp_f32_e32 v232, v116
	v_exp_f32_e32 v233, v117
	v_exp_f32_e32 v234, v118
	v_exp_f32_e32 v235, v119
	v_exp_f32_e32 v236, v120
	v_exp_f32_e32 v237, v121
	v_exp_f32_e32 v238, v122
	v_exp_f32_e32 v239, v123
	ds_read_b128 v[76:79], v182 offset:8192
	ds_read_b128 v[68:71], v182 offset:8704
	ds_read_b128 v[64:67], v182 offset:12288
	ds_read_b128 v[52:55], v182 offset:12800
	v_exp_f32_e32 v240, v124
	v_exp_f32_e32 v241, v125
	v_exp_f32_e32 v242, v126
	v_exp_f32_e32 v243, v127
	v_exp_f32_e32 v244, v132
	v_exp_f32_e32 v245, v133
	v_exp_f32_e32 v246, v134
	v_exp_f32_e32 v247, v135
	v_add_f32_e32 v188, v232, v233
	v_add_f32_e32 v189, v234, v235
	v_add_f32_e32 v190, v236, v237
	v_add_f32_e32 v191, v238, v239
	v_add_f32_e32 v188, v188, v240
	v_add_f32_e32 v189, v189, v241
	v_add_f32_e32 v190, v190, v242
	v_add_f32_e32 v191, v191, v243
	v_add_f32_e32 v188, v188, v244
	v_add_f32_e32 v189, v189, v245
	v_add_f32_e32 v190, v190, v246
	v_add_f32_e32 v191, v191, v247
	v_add_f32_e32 v188, v188, v189
	v_add_f32_e32 v190, v190, v191
	v_add_f32_e32 v190, v190, v188
	v_cmp_lt_f32_e32 vcc, 0x42800000, v190
	s_cbranch_vccnz .Lwin_int_s0
	v_add_f32_e32 v129, v155, v190
	v_cvt_pk_bf16_f32 v116, v232, v233
	v_cvt_pk_bf16_f32 v117, v234, v235
	v_cvt_pk_bf16_f32 v118, v236, v237
	v_cvt_pk_bf16_f32 v119, v238, v239
	v_cvt_pk_bf16_f32 v120, v240, v241
	v_cvt_pk_bf16_f32 v121, v242, v243
	v_cvt_pk_bf16_f32 v122, v244, v245
	v_cvt_pk_bf16_f32 v123, v246, v247
.Lwin_int_e1:
	v_exp_f32_e32 v232, v136
	v_exp_f32_e32 v233, v137
	v_exp_f32_e32 v234, v138
	v_exp_f32_e32 v235, v139
	v_exp_f32_e32 v236, v140
	v_exp_f32_e32 v237, v141
	v_exp_f32_e32 v238, v142
	v_exp_f32_e32 v239, v143
	v_exp_f32_e32 v240, v144
	v_exp_f32_e32 v241, v145
	v_exp_f32_e32 v242, v146
	v_exp_f32_e32 v243, v147
	v_exp_f32_e32 v244, v184
	v_exp_f32_e32 v245, v185
	v_exp_f32_e32 v246, v186
	v_exp_f32_e32 v247, v187
	v_add_f32_e32 v192, v232, v233
	v_add_f32_e32 v193, v234, v235
	v_add_f32_e32 v194, v236, v237
	v_add_f32_e32 v195, v238, v239
	v_add_f32_e32 v192, v192, v240
	v_add_f32_e32 v193, v193, v241
	v_add_f32_e32 v194, v194, v242
	v_add_f32_e32 v195, v195, v243
	v_add_f32_e32 v192, v192, v244
	v_add_f32_e32 v193, v193, v245
	v_add_f32_e32 v194, v194, v246
	v_add_f32_e32 v195, v195, v247
	v_add_f32_e32 v192, v192, v193
	v_add_f32_e32 v194, v194, v195
	v_add_f32_e32 v194, v194, v192
	v_cmp_lt_f32_e32 vcc, 0x42800000, v194
	s_cbranch_vccnz .Lwin_int_s1
	v_add_f32_e32 v128, v154, v194
	v_cvt_pk_bf16_f32 v136, v232, v233
	v_cvt_pk_bf16_f32 v137, v234, v235
	v_cvt_pk_bf16_f32 v138, v236, v237
	v_cvt_pk_bf16_f32 v139, v238, v239
	v_cvt_pk_bf16_f32 v140, v240, v241
	v_cvt_pk_bf16_f32 v141, v242, v243
	v_cvt_pk_bf16_f32 v142, v244, v245
	v_cvt_pk_bf16_f32 v143, v246, v247
	v_mov_b64_e32 v[158:159], v[156:157]
	s_waitcnt lgkmcnt(0)
	v_mfma_f32_16x16x32_bf16 v[48:51], v[80:83], v[116:119], v[48:51]
	v_mfma_f32_16x16x32_bf16 v[44:47], v[80:83], v[136:139], v[44:47]
	v_mfma_f32_16x16x32_bf16 v[40:43], v[72:75], v[116:119], v[40:43]
	v_mfma_f32_16x16x32_bf16 v[36:39], v[72:75], v[136:139], v[36:39]
	v_mfma_f32_16x16x32_bf16 v[32:35], v[60:63], v[116:119], v[32:35]
	v_mfma_f32_16x16x32_bf16 v[28:31], v[60:63], v[136:139], v[28:31]
	v_mfma_f32_16x16x32_bf16 v[24:27], v[56:59], v[116:119], v[24:27]
	v_mfma_f32_16x16x32_bf16 v[20:23], v[56:59], v[136:139], v[20:23]
	v_mfma_f32_16x16x32_bf16 v[92:95], v[76:79], v[120:123], v[48:51]
	v_mfma_f32_16x16x32_bf16 v[84:87], v[76:79], v[140:143], v[44:47]
	v_mfma_f32_16x16x32_bf16 v[104:107], v[68:71], v[120:123], v[40:43]
	v_mfma_f32_16x16x32_bf16 v[96:99], v[68:71], v[140:143], v[36:39]
	v_mfma_f32_16x16x32_bf16 v[100:103], v[64:67], v[120:123], v[32:35]
	v_mfma_f32_16x16x32_bf16 v[88:91], v[64:67], v[140:143], v[28:31]
	v_mfma_f32_16x16x32_bf16 v[112:115], v[52:55], v[120:123], v[24:27]
	v_mfma_f32_16x16x32_bf16 v[108:111], v[52:55], v[140:143], v[20:23]
	s_branch .LBB0_2733
